# cvhost: step-B wait relaxed to vmcnt(3) in active iterations so the HBM weight loads get two tile steps; always 3 loads per slot
# speedup vs baseline: 1.0230x; 1.0064x over previous
; __device__ __forceinline__ P0Desc p0_desc(int r, int lane, const P0Ptrs& a) {
;     const int kk = lane >> 3, n4 = (lane & 7) * 4; P0Desc d; d.gs = 1.f;
;     int kb, n, sc, nsrc, ldt; const float* W; bf16_t* WT; const float* ks;
;     if (r < F_O) { kb = r >> 6; n = 32 * (r & 63) + n4; sc = n; W = a.w_o; nsrc = 2048; WT = a.WoT; ldt = 2048; ks = (kb < 16) ? a.on_a : (a.on_c - 1024); }
;     else if ((r -= F_O) < F_UP) { kb = r / 352; n = 32 * (r % 352) + n4; sc = ((n >> 7) & 1) * DFF + (n >> 8) * 128 + (n & 127); W = a.w_up; nsrc = 2 * DFF; WT = a.WupT; ldt = 2048; ks = a.ffn_g; }
;     else if ((r -= F_UP) < F_DN) { kb = r >> 6; n = 32 * (r & 63) + n4; sc = n; W = a.w_dn; nsrc = 2048; WT = a.WdT; ldt = DFF; ks = nullptr; }
;     else if ((r -= F_DN) < F_IN) { kb = r >> 7; n = 32 * (r & 127) + n4;
;         if (n < 1024) sc = n; else if (n < 2048) sc = n + 64; else sc = (((n >> 7) & 1) ? 3136 : 2112) + 128 * ((n - 2048) >> 8) + (n & 127);
;         W = a.w_in; nsrc = INW; WT = a.WinT; ldt = 2048; ks = a.attn_g; }
;     else if ((r -= F_IN) < F_Q) { kb = r >> 5; n = 32 * (6 * ((r & 31) >> 2) + (r & 3)) + n4; sc = n; W = a.w_qb; nsrc = 1536; WT = a.WqT; ldt = 2048; ks = a.qa_g; d.gs = QSCALE; }
;     else { r -= F_Q; kb = r >> 6; n = 32 * (r & 63) + n4; sc = n; W = a.w_kvb; nsrc = 2048; WT = a.WkvT; ldt = 2048; ks = a.kva_g; }
;     const int k0 = 64 * kb + 8 * kk;
;     d.src = W + (size_t)k0 * nsrc + sc; d.nsrc = nsrc; d.dst = WT + (size_t)n * ldt + k0; d.ldt = ldt; d.ks = ks ? ks + k0 : nullptr;
;     return d;
; }
; __device__ __forceinline__ int p0_super(int s, int q) {
;     int base, nbw;
;     if (s < F_O / 4) { base = 0; nbw = 64; }
;     else if ((s -= F_O / 4) < F_UP / 4) { base = F_O; nbw = 352; }
;     else if ((s -= F_UP / 4) < F_DN / 4) { base = F_O + F_UP; nbw = 64; }
;     else if ((s -= F_DN / 4) < F_IN / 4) { base = F_O + F_UP + F_DN; nbw = 128; }
;     else if ((s -= F_IN / 4) < F_Q / 4) { base = F_O + F_UP + F_DN + F_IN; nbw = 32; }
;     else { s -= F_Q / 4; base = F_O + F_UP + F_DN + F_IN + F_Q; nbw = 64; }
;     return base + ((s / nbw) * 4 + q) * nbw + (s % nbw);
; }
; template <int NB>
; __device__ __forceinline__ void p0_batch(int it0, int stride, int lane, const P0Ptrs& a) {
;     f32x4 v[NB][8], s0[NB], s1[NB]; P0Desc d[NB];
; #pragma unroll
.Lcv_s2done:
.Lcv_loads:
	global_load_dwordx4 v[240:243], v237, s[88:89] nt
	s_add_u32 s98, s88, s90
	s_addc_u32 s99, s89, 0
	global_load_dwordx4 v[250:253], v237, s[98:99] nt
	global_load_dwordx2 v[244:245], v239, s[94:95]
	s_add_u32 s94, s94, 8
	s_addc_u32 s95, s95, 0
	s_lshl_b32 s98, s90, 1
	s_add_u32 s88, s88, s98
	s_addc_u32 s89, s89, 0
	s_and_b32 s98, s87, 3
	s_cmp_lg_u32 s98, 3
	s_cbranch_scc1 .Lcv_inc
	s_cmp_gt_u32 s87, 18
	s_cbranch_scc1 .Lcv_inc
	s_add_i32 s99, s32, 1
	s_movk_i32 s98, 0x78
	s_cmp_lt_u32 s99, 7
	s_cselect_b32 s98, 0x60, s98
	s_cmp_eq_u32 s99, 0
	s_cselect_b32 s98, 0x50, s98
	s_cselect_b32 s99, 0, 0x58
	s_load_dwordx2 s[88:89], s[100:101], s98
	s_cmp_eq_u32 s99, 0
	s_cbranch_scc0 .Lcv_s1b_s
	s_bfe_u32 s99, s2, 0x50003
	s_cmp_lt_u32 s99, 16
	s_cselect_b32 s99, 64, 0x48

; #define SBAR() __builtin_amdgcn_sched_barrier(0)
; #define DMA_K(t, bf) do { if (ABL & 8) break; const char* kb_ = Kt + (size_t)(t) * KSTEP; LAS unsigned char* kd_ = Kl + (bf) * SHM_K + wid * 1024; \
;     glds16(kb_ + voffK, kd_); glds16(kb_ + 128 + voffK, kd_ + 8192); glds16(Pt + (size_t)(t) * PSTEP + voffP, kd_ + 16384); } while (0)
; #define DMA_V(t, bf) do { if (ABL & 8) break; const char* vb_ = Kt + 256 + (size_t)(t) * KSTEP; LAS unsigned char* vd_ = Vl + (bf) * SHM_V + wid * 1024; \
;     glds16(vb_ + voffV, vd_); glds16(vb_ + (size_t)32 * LDKV * 2 + voffV, vd_ + 8192); } while (0)
; #define END_STEP() do { if (!(ABL & 8)) { asm volatile("s_waitcnt vmcnt(0)" ::: "memory"); __syncthreads(); } } while (0)
; #define RESC(a) do { if (__any((a) < 1.f)) { if (hi == 0) al_l[r32] = (a); asm volatile("s_waitcnt lgkmcnt(0)" ::: "memory"); \
;     _Pragma("unroll") for (int d = 0; d < 4; ++d) _Pragma("unroll") for (int r = 0; r < 16; ++r) o[d][r] *= al_l[crow(r, hi)]; } } while (0)
; #define PV_TILE(VB, C0, C1, alC, PAR) do { s16x4 va_[8], vb_[8]; float ma_ = 0.f, mb_ = 0.f, mn_ = 0.f; VRD8(VB, 0, va_); SBAR(); \
;     PV_BLK(VB, 0, va_, vb_, C0, C1, PAR); if (PAR) { DECIDE(alC); } SBAR(); \
;     PV_BLK(VB, 1, vb_, va_, C0, C1, PAR); PV_BLK(VB, 2, va_, vb_, C0, C1, PAR); PV_BLK(VB, 3, vb_, va_, C0, C1, PAR); } while (0)
; template <int ABL> __device__ __forceinline__ void attn_unit(int b, int h, int qb, const bf16_t* Q, const bf16_t* KV, const bf16_t* KPE, bf16_t* MG, float* ssqa, LAS unsigned char* L) {
;     ...
;     END_STEP(); DMA_K(j + 2, 1); DMA_V(j + 1, 0);
;     SBAR(); QK_TILE(Kl, pA0, pA1, pB0, pB1, alB, true);
;     SBAR(); PAR_ONLY(pA0, pA1, alA); SBAR(); PV_TILE(Vp + SHM_V, pA0, pA1, alA, false);
;     RESC(alA);
;     END_STEP(); if (j + 3 < NT) DMA_K(j + 3, 0); DMA_V(j + 2, 1);
.LBB0_764:
	s_add_i32 s98, s87, -1
	s_cmp_lt_u32 s98, 20
	s_cbranch_scc1 .Lcv_w3
	s_waitcnt vmcnt(0)
	s_branch .Lcv_wd
.Lcv_w3:
	s_waitcnt vmcnt(3)
.Lcv_wd:
	v_pk_add_f32 v[130:131], v[84:85], v[140:141] op_sel_hi:[1,0] neg_lo:[0,1] neg_hi:[0,1]
	v_pk_add_f32 v[132:133], v[86:87], v[140:141] op_sel_hi:[1,0] neg_lo:[0,1] neg_hi:[0,1]
	v_pk_add_f32 v[160:161], v[88:89], v[140:141] op_sel_hi:[1,0] neg_lo:[0,1] neg_hi:[0,1]
	v_pk_add_f32 v[158:159], v[90:91], v[140:141] op_sel_hi:[1,0] neg_lo:[0,1] neg_hi:[0,1]
	v_pk_add_f32 v[156:157], v[92:93], v[140:141] op_sel_hi:[1,0] neg_lo:[0,1] neg_hi:[0,1]
	v_pk_add_f32 v[154:155], v[94:95], v[140:141] op_sel_hi:[1,0] neg_lo:[0,1] neg_hi:[0,1]
	v_pk_add_f32 v[152:153], v[96:97], v[140:141] op_sel_hi:[1,0] neg_lo:[0,1] neg_hi:[0,1]
	v_pk_add_f32 v[150:151], v[98:99], v[140:141] op_sel_hi:[1,0] neg_lo:[0,1] neg_hi:[0,1]
	s_cmp_gt_u32 s81, 60
	s_mov_b64 s[54:55], -1
	s_barrier
	s_cbranch_scc1 .LBB0_766
	s_mov_b32 m0, s59
	v_lshl_add_u64 v[84:85], v[112:113], 0, s[46:47]
	global_load_lds_dwordx4 v[84:85], off
	v_lshl_add_u64 v[84:85], v[112:113], 0, s[48:49]
	s_mov_b32 m0, s60
	v_lshl_add_u64 v[144:145], v[144:145], 0, s[10:11]
	global_load_lds_dwordx4 v[84:85], off
	v_lshl_add_u64 v[84:85], v[136:137], 0, s[50:51]
	s_mov_b32 m0, s61
	v_lshl_add_u64 v[146:147], v[146:147], 0, s[8:9]
	global_load_lds_dwordx4 v[84:85], off
	v_lshl_add_u64 v[84:85], v[134:135], 0, s[62:63]
	s_mov_b32 m0, s79
	v_lshl_add_u64 v[148:149], v[148:149], 0, s[8:9]
	global_load_lds_dwordx4 v[84:85], off
	v_lshl_add_u64 v[84:85], v[134:135], 0, s[64:65]
	s_mov_b32 m0, s80
	s_add_i32 s81, s81, 2
	global_load_lds_dwordx4 v[84:85], off
	s_mov_b64 s[54:55], 0
